# hazard-clean build: one more wait state between the VALU-read barrier base and the conversion-count atomic (0 hazards in the linear checker incl. store-data WAR)
# baseline (speedup 1.0000x reference)
; __device__ __forceinline__ unsigned xb_ld(unsigned* p) { return __hip_atomic_load(p, __ATOMIC_RELAXED, __HIP_MEMORY_SCOPE_AGENT); }
; __device__ __forceinline__ unsigned xb_add(unsigned* p, unsigned v) { return __hip_atomic_fetch_add(p, v, __ATOMIC_RELAXED, __HIP_MEMORY_SCOPE_AGENT); }
.Lgb5_conv:
	v_readlane_b32 s8, v254, 6
	v_readlane_b32 s9, v254, 7
	s_add_u32 s8, s8, 0x12c00
	s_addc_u32 s9, s9, 0
	s_nop 2
	global_atomic_add v0, v1, s[8:9]
